# same single B half-tile stage move (second -> third segment) also in the w_in main loop, waits vmcnt 8->6 and relaxed 24->22; on top of v72
# baseline (speedup 1.0000x reference)
.Lrx_skip_12:
	s_waitcnt vmcnt(24)
	s_waitcnt lgkmcnt(0)
	s_barrier
	s_setprio 1
	v_mfma_f32_16x16x32_bf16 v[126:129], v[130:133], v[218:221], v[126:129]
	v_mfma_f32_16x16x32_bf16 v[122:125], v[152:155], v[218:221], v[122:125]
	v_mfma_f32_16x16x32_bf16 v[110:113], v[130:133], v[226:229], v[110:113]
	v_mfma_f32_16x16x32_bf16 v[106:109], v[152:155], v[226:229], v[106:109]
	v_mfma_f32_16x16x32_bf16 v[94:97], v[130:133], v[234:237], v[94:97]
	v_mfma_f32_16x16x32_bf16 v[90:93], v[152:155], v[234:237], v[90:93]
	v_mfma_f32_16x16x32_bf16 v[78:81], v[130:133], v[242:245], v[78:81]
	v_mfma_f32_16x16x32_bf16 v[74:77], v[152:155], v[242:245], v[74:77]
	v_mfma_f32_16x16x32_bf16 v[126:129], v[148:151], v[222:225], v[126:129]
	v_mfma_f32_16x16x32_bf16 v[122:125], v[182:185], v[222:225], v[122:125]
	v_mfma_f32_16x16x32_bf16 v[110:113], v[148:151], v[230:233], v[110:113]
	v_mfma_f32_16x16x32_bf16 v[106:109], v[182:185], v[230:233], v[106:109]
	v_mfma_f32_16x16x32_bf16 v[94:97], v[148:151], v[238:241], v[94:97]
	v_mfma_f32_16x16x32_bf16 v[90:93], v[182:185], v[238:241], v[90:93]
	v_mfma_f32_16x16x32_bf16 v[78:81], v[148:151], v[246:249], v[78:81]
	v_mfma_f32_16x16x32_bf16 v[74:77], v[182:185], v[246:249], v[74:77]
	s_setprio 0
	s_setprio 1
	v_mfma_f32_16x16x32_bf16 v[118:121], v[186:189], v[218:221], v[118:121]
	v_mfma_f32_16x16x32_bf16 v[114:117], v[210:213], v[218:221], v[114:117]
	v_mfma_f32_16x16x32_bf16 v[102:105], v[186:189], v[226:229], v[102:105]
	v_mfma_f32_16x16x32_bf16 v[98:101], v[210:213], v[226:229], v[98:101]
	v_mfma_f32_16x16x32_bf16 v[86:89], v[186:189], v[234:237], v[86:89]
	v_mfma_f32_16x16x32_bf16 v[82:85], v[210:213], v[234:237], v[82:85]
	v_mfma_f32_16x16x32_bf16 v[70:73], v[186:189], v[242:245], v[70:73]
	v_mfma_f32_16x16x32_bf16 v[66:69], v[210:213], v[242:245], v[66:69]
	v_mfma_f32_16x16x32_bf16 v[118:121], v[190:193], v[222:225], v[118:121]
	v_mfma_f32_16x16x32_bf16 v[114:117], v[214:217], v[222:225], v[114:117]
	v_mfma_f32_16x16x32_bf16 v[102:105], v[190:193], v[230:233], v[102:105]
	v_mfma_f32_16x16x32_bf16 v[98:101], v[214:217], v[230:233], v[98:101]
	v_mfma_f32_16x16x32_bf16 v[86:89], v[190:193], v[238:241], v[86:89]
	v_mfma_f32_16x16x32_bf16 v[82:85], v[214:217], v[238:241], v[82:85]
	v_mfma_f32_16x16x32_bf16 v[70:73], v[190:193], v[246:249], v[70:73]
	v_mfma_f32_16x16x32_bf16 v[66:69], v[214:217], v[246:249], v[66:69]
	s_setprio 0
	s_barrier
	ds_read_b128 v[218:221], v146 offset:16384
	ds_read_b128 v[222:225], v146 offset:17408
	ds_read_b128 v[226:229], v146 offset:18432
	ds_read_b128 v[230:233], v146 offset:19456
	ds_read_b128 v[234:237], v146 offset:20480
	ds_read_b128 v[238:241], v146 offset:21504
	ds_read_b128 v[242:245], v146 offset:22528
	ds_read_b128 v[246:249], v146 offset:23552
	s_mov_b32 m0, s56
	s_nop 0
	global_load_lds_dwordx4 v137, s[46:47]
	s_mov_b32 m0, s57
	s_nop 0
	global_load_lds_dwordx4 v139, s[46:47]
	s_nop 0
	s_mov_b32 m0, s39
	s_nop 0
	global_load_lds_dwordx4 v136, s[50:51]
	s_nop 0
	s_mov_b32 m0, s60
	s_nop 0
	global_load_lds_dwordx4 v138, s[50:51]
	s_cmp_lg_u32 s18, 0
	s_cbranch_scc1 .Lrx_skip_13
	s_waitcnt vmcnt(6)
.Lrx_skip_13:
	s_waitcnt vmcnt(22)
	s_waitcnt lgkmcnt(0)
	s_barrier
	s_setprio 1
	v_mfma_f32_16x16x32_bf16 v[62:65], v[130:133], v[218:221], v[62:65]
	v_mfma_f32_16x16x32_bf16 v[58:61], v[152:155], v[218:221], v[58:61]
	v_mfma_f32_16x16x32_bf16 v[46:49], v[130:133], v[226:229], v[46:49]
	v_mfma_f32_16x16x32_bf16 v[42:45], v[152:155], v[226:229], v[42:45]
	v_mfma_f32_16x16x32_bf16 v[30:33], v[130:133], v[234:237], v[30:33]
	v_mfma_f32_16x16x32_bf16 v[26:29], v[152:155], v[234:237], v[26:29]
	v_mfma_f32_16x16x32_bf16 v[14:17], v[130:133], v[242:245], v[14:17]
	v_mfma_f32_16x16x32_bf16 v[10:13], v[152:155], v[242:245], v[10:13]
	v_mfma_f32_16x16x32_bf16 v[62:65], v[148:151], v[222:225], v[62:65]
	v_mfma_f32_16x16x32_bf16 v[58:61], v[182:185], v[222:225], v[58:61]
	v_mfma_f32_16x16x32_bf16 v[46:49], v[148:151], v[230:233], v[46:49]
	v_mfma_f32_16x16x32_bf16 v[42:45], v[182:185], v[230:233], v[42:45]
	v_mfma_f32_16x16x32_bf16 v[30:33], v[148:151], v[238:241], v[30:33]
	v_mfma_f32_16x16x32_bf16 v[26:29], v[182:185], v[238:241], v[26:29]
	v_mfma_f32_16x16x32_bf16 v[14:17], v[148:151], v[246:249], v[14:17]
	v_mfma_f32_16x16x32_bf16 v[10:13], v[182:185], v[246:249], v[10:13]
	s_setprio 0
	s_setprio 1
	v_mfma_f32_16x16x32_bf16 v[54:57], v[186:189], v[218:221], v[54:57]
	v_mfma_f32_16x16x32_bf16 v[50:53], v[210:213], v[218:221], v[50:53]
	v_mfma_f32_16x16x32_bf16 v[38:41], v[186:189], v[226:229], v[38:41]
	v_mfma_f32_16x16x32_bf16 v[34:37], v[210:213], v[226:229], v[34:37]
	v_mfma_f32_16x16x32_bf16 v[22:25], v[186:189], v[234:237], v[22:25]
	v_mfma_f32_16x16x32_bf16 v[18:21], v[210:213], v[234:237], v[18:21]
	v_mfma_f32_16x16x32_bf16 v[6:9], v[186:189], v[242:245], v[6:9]
	v_mfma_f32_16x16x32_bf16 v[2:5], v[210:213], v[242:245], v[2:5]
	v_mfma_f32_16x16x32_bf16 v[54:57], v[190:193], v[222:225], v[54:57]
	v_mfma_f32_16x16x32_bf16 v[50:53], v[214:217], v[222:225], v[50:53]
	v_mfma_f32_16x16x32_bf16 v[38:41], v[190:193], v[230:233], v[38:41]
	v_mfma_f32_16x16x32_bf16 v[34:37], v[214:217], v[230:233], v[34:37]
	v_mfma_f32_16x16x32_bf16 v[22:25], v[190:193], v[238:241], v[22:25]
	v_mfma_f32_16x16x32_bf16 v[18:21], v[214:217], v[238:241], v[18:21]
	v_mfma_f32_16x16x32_bf16 v[6:9], v[190:193], v[246:249], v[6:9]
	v_mfma_f32_16x16x32_bf16 v[2:5], v[214:217], v[246:249], v[2:5]
	s_setprio 0
	s_barrier
	v_add_u32_e32 v147, 0x18000, v145
	ds_read_b128 v[130:133], v147
	ds_read_b128 v[148:151], v147 offset:1024
	ds_read_b128 v[152:155], v147 offset:2048
	ds_read_b128 v[182:185], v147 offset:3072
	v_add_u32_e32 v147, 0x1c000, v145
	ds_read_b128 v[186:189], v147
	ds_read_b128 v[190:193], v147 offset:1024
	ds_read_b128 v[210:213], v147 offset:2048
	ds_read_b128 v[214:217], v147 offset:3072
	ds_read_b128 v[218:221], v146 offset:32768
	ds_read_b128 v[222:225], v146 offset:33792
	ds_read_b128 v[226:229], v146 offset:34816
	ds_read_b128 v[230:233], v146 offset:35840
	ds_read_b128 v[234:237], v146 offset:36864
	ds_read_b128 v[238:241], v146 offset:37888
	ds_read_b128 v[242:245], v146 offset:38912
	ds_read_b128 v[246:249], v146 offset:39936
	s_add_u32 s8, s46, 0x40000
	s_addc_u32 s9, s47, 0
	s_mov_b32 m0, s58
	s_nop 0
	global_load_lds_dwordx4 v137, s[8:9]
	s_nop 0
	s_mov_b32 m0, s59
	s_nop 0
	global_load_lds_dwordx4 v139, s[8:9]
	s_nop 0
	s_add_u32 s8, s50, 0x40000
	s_addc_u32 s9, s51, 0
	s_mov_b32 m0, s61
	s_nop 0
	global_load_lds_dwordx4 v136, s[8:9]
	s_nop 0
	s_mov_b32 m0, s62
	s_nop 0
	global_load_lds_dwordx4 v138, s[8:9]
	s_cmp_lg_u32 s18, 0
	s_cbranch_scc1 .Lrx_skip_14
	s_waitcnt vmcnt(8)
